# plus diff-attention loop: exp/sum/cvt per 16-key slice interleaved with PV MFMAs, V fragments streamed with ds_read_b64
# speedup vs baseline: 1.0340x; 1.0021x over previous
; #define LAS __attribute__((address_space(3)))
; #define MFMA32(a, b, c) __builtin_amdgcn_mfma_f32_32x32x16_bf16((a), (b), (c), 0, 0, 0)
; template <bool SUM> __device__ __forceinline__ bool softmax_tile(f32x16& pa, f32x16& pb, float& m, float& l, f32x16& o0, f32x16& o1, bool first) {
;     ...
; #pragma unroll
;     for (int r = 0; r < 16; ++r) { pa[r] = __builtin_amdgcn_exp2f(pa[r]); pb[r] = __builtin_amdgcn_exp2f(pb[r]); }
;     if (SUM) l += sum16(pa) + sum16(pb);
;     ...
;                 for (int ks = 0; ks < 4; ++ks) pf[mp][ks] = pack_frag(p[ks >> 1], ks & 1);
;             }
;             const LAS unsigned char* vb = bb + KB + r32 * VP + 8 * hi;
; #pragma unroll
;             for (int dh = 0; dh < 2; ++dh) {
;                 bf16x8 vf[4];
; #pragma unroll
;                 for (int ks = 0; ks < 4; ++ks) {
;                     const u32x2 v0 = *(const LAS u32x2*)(vb + dh * 32 * VP + 32 * ks), v1 = *(const LAS u32x2*)(vb + dh * 32 * VP + 32 * ks + 16);
;                     const u32x4 vv = {v0.x, v0.y, v1.x, v1.y}; vf[ks] = __builtin_bit_cast(bf16x8, vv); }
;                 __builtin_amdgcn_sched_barrier(0);
; #pragma unroll
;                 for (int ks = 0; ks < 4; ++ks)
; #pragma unroll
;                     for (int mp = 0; mp < NM; ++mp) o[mp][dh] = MFMA32(vf[ks], pf[mp][ks], o[mp][dh]);
.LBB0_199:
	s_or_b64 exec, exec, s[48:49]
	v_add3_u32 v0, s20, v232, v233
	v_add_u32_e32 v0, 0x2000, v0
	ds_read_b64 v[4:5], v0 offset:1024
	ds_read_b64 v[6:7], v0 offset:1040
	ds_read_b64 v[8:9], v0 offset:5376
	ds_read_b64 v[10:11], v0 offset:5392
	ds_read_b64 v[12:13], v0 offset:1056
	ds_read_b64 v[14:15], v0 offset:1072
	ds_read_b64 v[180:181], v0 offset:5408
	ds_read_b64 v[182:183], v0 offset:5424
	v_exp_f32_e32 v80, v80
	v_exp_f32_e32 v81, v81
	v_exp_f32_e32 v82, v82
	v_exp_f32_e32 v83, v83
	v_exp_f32_e32 v84, v84
	v_exp_f32_e32 v85, v85
	v_exp_f32_e32 v86, v86
	v_exp_f32_e32 v87, v87
	v_add_f32_e32 v0, v80, v81
	v_add_f32_e32 v1, v82, v83
	v_add_f32_e32 v0, v1, v0
	v_add_f32_e32 v1, v84, v85
	v_add_f32_e32 v2, v86, v87
	v_add_f32_e32 v1, v1, v2
	v_add_f32_e32 v176, v1, v0
	v_cvt_pk_bf16_f32 v80, v80, v81
	v_cvt_pk_bf16_f32 v81, v82, v83
	v_cvt_pk_bf16_f32 v82, v84, v85
	v_cvt_pk_bf16_f32 v83, v86, v87
	v_exp_f32_e32 v112, v112
	v_exp_f32_e32 v113, v113
	v_exp_f32_e32 v114, v114
	s_waitcnt lgkmcnt(4)
	v_mfma_f32_32x32x16_bf16 v[32:47], v[4:7], v[80:83], v[32:47]
	v_exp_f32_e32 v115, v115
	v_exp_f32_e32 v116, v116
	v_exp_f32_e32 v117, v117
	v_exp_f32_e32 v118, v118
	v_mfma_f32_32x32x16_bf16 v[64:79], v[8:11], v[80:83], v[64:79]
	v_exp_f32_e32 v119, v119
	v_add_f32_e32 v0, v112, v113
	v_add_f32_e32 v1, v114, v115
	v_add_f32_e32 v0, v1, v0
	v_add_f32_e32 v1, v116, v117
	v_add_f32_e32 v2, v118, v119
	v_add_f32_e32 v1, v1, v2
	v_add_f32_e32 v178, v1, v0
	v_cvt_pk_bf16_f32 v112, v112, v113
	v_cvt_pk_bf16_f32 v113, v114, v115
	v_cvt_pk_bf16_f32 v114, v116, v117
	v_cvt_pk_bf16_f32 v115, v118, v119
	v_exp_f32_e32 v88, v88
	v_exp_f32_e32 v89, v89
	v_exp_f32_e32 v90, v90
	v_mfma_f32_32x32x16_bf16 v[16:31], v[4:7], v[112:115], v[16:31]
	v_exp_f32_e32 v91, v91
	v_exp_f32_e32 v92, v92
	v_exp_f32_e32 v93, v93
	v_exp_f32_e32 v94, v94
	v_mfma_f32_32x32x16_bf16 v[48:63], v[8:11], v[112:115], v[48:63]
	v_exp_f32_e32 v95, v95
	v_add_f32_e32 v0, v88, v89
	v_add_f32_e32 v1, v90, v91
	v_add_f32_e32 v0, v1, v0
	v_add_f32_e32 v1, v92, v93
	v_add_f32_e32 v2, v94, v95
	v_add_f32_e32 v1, v1, v2
	v_add_f32_e32 v176, v0, v176
	v_add_f32_e32 v176, v1, v176
	v_cvt_pk_bf16_f32 v88, v88, v89
	v_cvt_pk_bf16_f32 v89, v90, v91
	v_cvt_pk_bf16_f32 v90, v92, v93
	v_cvt_pk_bf16_f32 v91, v94, v95
	v_add3_u32 v0, s20, v232, v233
	v_add_u32_e32 v0, 0x2000, v0
	ds_read_b64 v[4:5], v0 offset:1088
	ds_read_b64 v[6:7], v0 offset:1104
	ds_read_b64 v[8:9], v0 offset:5440
	ds_read_b64 v[10:11], v0 offset:5456
	v_exp_f32_e32 v120, v120
	v_exp_f32_e32 v121, v121
	v_exp_f32_e32 v122, v122
	s_waitcnt lgkmcnt(4)
	v_mfma_f32_32x32x16_bf16 v[32:47], v[12:15], v[88:91], v[32:47]
	v_exp_f32_e32 v123, v123
	v_exp_f32_e32 v124, v124
	v_exp_f32_e32 v125, v125
	v_exp_f32_e32 v126, v126
	v_mfma_f32_32x32x16_bf16 v[64:79], v[180:183], v[88:91], v[64:79]
	v_exp_f32_e32 v127, v127
	v_add_f32_e32 v0, v120, v121
	v_add_f32_e32 v1, v122, v123
	v_add_f32_e32 v0, v1, v0
	v_add_f32_e32 v1, v124, v125
	v_add_f32_e32 v2, v126, v127
	v_add_f32_e32 v1, v1, v2
	v_add_f32_e32 v178, v0, v178
	v_add_f32_e32 v178, v1, v178
	v_cvt_pk_bf16_f32 v120, v120, v121
	v_cvt_pk_bf16_f32 v121, v122, v123
	v_cvt_pk_bf16_f32 v122, v124, v125
	v_cvt_pk_bf16_f32 v123, v126, v127
	v_exp_f32_e32 v96, v96
	v_exp_f32_e32 v97, v97
	v_exp_f32_e32 v98, v98
	v_mfma_f32_32x32x16_bf16 v[16:31], v[12:15], v[120:123], v[16:31]
	v_exp_f32_e32 v99, v99
	v_exp_f32_e32 v100, v100
	v_exp_f32_e32 v101, v101
	v_exp_f32_e32 v102, v102
	v_mfma_f32_32x32x16_bf16 v[48:63], v[180:183], v[120:123], v[48:63]
	v_exp_f32_e32 v103, v103
	v_add_f32_e32 v0, v96, v97
	v_add_f32_e32 v1, v98, v99
	v_add_f32_e32 v0, v1, v0
	v_add_f32_e32 v1, v100, v101
	v_add_f32_e32 v2, v102, v103
	v_add_f32_e32 v1, v1, v2
	v_add_f32_e32 v177, v1, v0
	v_cvt_pk_bf16_f32 v96, v96, v97
	v_cvt_pk_bf16_f32 v97, v98, v99
	v_cvt_pk_bf16_f32 v98, v100, v101
	v_cvt_pk_bf16_f32 v99, v102, v103
	v_add3_u32 v0, s20, v232, v233
	v_add_u32_e32 v0, 0x2000, v0
	ds_read_b64 v[12:13], v0 offset:1120
	ds_read_b64 v[14:15], v0 offset:1136
	ds_read_b64 v[180:181], v0 offset:5472
	ds_read_b64 v[182:183], v0 offset:5488
	v_exp_f32_e32 v128, v128
	v_exp_f32_e32 v129, v129
	v_exp_f32_e32 v130, v130
	s_waitcnt lgkmcnt(4)
	v_mfma_f32_32x32x16_bf16 v[32:47], v[4:7], v[96:99], v[32:47]
	v_exp_f32_e32 v131, v131
	v_exp_f32_e32 v132, v132
	v_exp_f32_e32 v133, v133
	v_exp_f32_e32 v134, v134
	v_mfma_f32_32x32x16_bf16 v[64:79], v[8:11], v[96:99], v[64:79]
	v_exp_f32_e32 v135, v135
	v_add_f32_e32 v0, v128, v129
	v_add_f32_e32 v1, v130, v131
	v_add_f32_e32 v0, v1, v0
	v_add_f32_e32 v1, v132, v133
	v_add_f32_e32 v2, v134, v135
	v_add_f32_e32 v1, v1, v2
	v_add_f32_e32 v179, v1, v0
	v_cvt_pk_bf16_f32 v128, v128, v129
	v_cvt_pk_bf16_f32 v129, v130, v131
	v_cvt_pk_bf16_f32 v130, v132, v133
	v_cvt_pk_bf16_f32 v131, v134, v135
	v_exp_f32_e32 v104, v104
	v_exp_f32_e32 v105, v105
	v_exp_f32_e32 v106, v106
	v_mfma_f32_32x32x16_bf16 v[16:31], v[4:7], v[128:131], v[16:31]
	v_exp_f32_e32 v107, v107
	v_exp_f32_e32 v108, v108
	v_exp_f32_e32 v109, v109
	v_exp_f32_e32 v110, v110
	v_mfma_f32_32x32x16_bf16 v[48:63], v[8:11], v[128:131], v[48:63]
	v_exp_f32_e32 v111, v111
	v_add_f32_e32 v0, v104, v105
	v_add_f32_e32 v1, v106, v107
	v_add_f32_e32 v0, v1, v0
	v_add_f32_e32 v1, v108, v109
	v_add_f32_e32 v2, v110, v111
	v_add_f32_e32 v1, v1, v2
	v_add_f32_e32 v177, v0, v177
	v_add_f32_e32 v177, v1, v177
	v_add_f32_e32 v0, v177, v176
	v_add_f32_e32 v236, v236, v0
	v_cvt_pk_bf16_f32 v104, v104, v105
	v_cvt_pk_bf16_f32 v105, v106, v107
	v_cvt_pk_bf16_f32 v106, v108, v109
	v_cvt_pk_bf16_f32 v107, v110, v111
	v_exp_f32_e32 v136, v136
	v_exp_f32_e32 v137, v137
	v_exp_f32_e32 v138, v138
	s_waitcnt lgkmcnt(0)
	v_mfma_f32_32x32x16_bf16 v[32:47], v[12:15], v[104:107], v[32:47]
	v_exp_f32_e32 v139, v139
	v_exp_f32_e32 v140, v140
	v_exp_f32_e32 v141, v141
	v_exp_f32_e32 v142, v142
	v_mfma_f32_32x32x16_bf16 v[64:79], v[180:183], v[104:107], v[64:79]
	v_exp_f32_e32 v143, v143
	v_add_f32_e32 v0, v136, v137
	v_add_f32_e32 v1, v138, v139
	v_add_f32_e32 v0, v1, v0
	v_add_f32_e32 v1, v140, v141
	v_add_f32_e32 v2, v142, v143
	v_add_f32_e32 v1, v1, v2
	v_add_f32_e32 v179, v0, v179
	v_add_f32_e32 v179, v1, v179
	v_add_f32_e32 v0, v179, v178
	v_add_f32_e32 v228, v228, v0
	v_cvt_pk_bf16_f32 v136, v136, v137
	v_cvt_pk_bf16_f32 v137, v138, v139
	v_cvt_pk_bf16_f32 v138, v140, v141
	v_cvt_pk_bf16_f32 v139, v142, v143
	v_mfma_f32_32x32x16_bf16 v[16:31], v[12:15], v[136:139], v[16:31]
	v_mfma_f32_32x32x16_bf16 v[48:63], v[180:183], v[136:139], v[48:63]
	s_andn2_b64 vcc, exec, s[80:81]
	s_cbranch_vccnz .LBB0_175
